# one static s_setprio 1 for waves 4-7 during the two mixer passes (reset to 0 at the pass end)
# speedup vs baseline: 1.0154x; 1.0154x over previous
; #define LAS __attribute__((address_space(3)))
; #define WAVE_ITEM_LOOP(COND, CALL) do { \
;         for (int it = blockIdx.x * 8 + wave; it < BATCH * NCH * 16; it += gridDim.x * 8) { \
;             const int bc = it >> 4, k = ((it & 15) + (it >> 8) + 4 * (it >> 11)) & 15, b = bc / NCH, ck_ = bc % NCH; if (!(COND)) continue; \
;             int lane = c.tid & 63; asm volatile("" : "+v"(lane)); CALL; } } while (0)
; template <int pass>
; __device__ __forceinline__ void mix_phase(const Args& a, const MixCtx& c) {
;     ...
;     const int wave = __builtin_amdgcn_readfirstlane(c.tid >> 6);
;     LAS unsigned char* wl = c.lds + wave * WLDS;
;     ...
; #pragma unroll 1
;     for (int st = 0; st < 3; ++st) {
;         const int kind = (st + (wave >> 2)) % 3;
;         if (kind == 0) { if (pass == 1) WAVE_ITEM_LOOP(k >= 8 && k < 12, w_ret_m1(c.ws, c.proj, wl, b, ck_, k - 8, lane)); else WAVE_ITEM_LOOP(k >= 8 && k < 12, w_ret_m3(a, c.l, c.ws, c.proj, c.y, wl, b, ck_, k - 8, lane)); }
;         else if (kind == 1) { if (pass == 1) WAVE_ITEM_LOOP(k >= 12, w_hg_m1(a, c.l, c.ws, c.proj, wl, b, ck_, k - 12, lane)); else WAVE_ITEM_LOOP(k >= 12, w_hg_m3(a, c.l, c.ws, c.proj, c.y, wl, b, ck_, k - 12, lane)); }
;         else { if (pass == 1) WAVE_ITEM_LOOP(k < 8, w_lru_m1(a, c.l, c.ws, c.proj, c.y, wl, b, ck_, k, lane)); else WAVE_ITEM_LOOP(k < 8, w_lru_m3(c.ws, c.proj, c.y, b, ck_, k, lane)); }
; __global__ void __launch_bounds__(NTHREADS, 2) fwd_kernel(Args a) {
;     ...
;             } else if (k >= 1 && k <= 3) {
;                 MixCtx c; c.l = l; c.ws = ws; c.sb = (unsigned char*)a.out; c.lds = lds; c.tid = tid; c.lane = tid & 63; c.wave = tid >> 6; c.proj = r1; c.y = yb;
;                 if (k == 2) { ON_M2(mix_m2(c);)
;     ...
;                     __syncthreads(); mix_m2(c);
;     ...
;                 } else if (k == 1) { ON_MX(mix_phase<1>(a, c);) } else { ON_MX(mix_phase<3>(a, c);) }
.LBB0_167:
	s_cmp_lt_i32 s2, 2
	s_mov_b64 s[4:5], -1
	s_cbranch_scc1 .LBB0_500
	s_load_dwordx4 s[48:51], s[0:1], 0xa0
	s_cmp_lg_u32 s2, 2
	v_readlane_b32 s80, v255, 20
	v_readlane_b32 s81, v255, 21
	s_mov_b32 s91, 0x8000
	s_movk_i32 s92, 0x7fff
	s_movk_i32 s93, 0xf000
	s_movk_i32 s96, 0x80
	s_mov_b32 s97, 0xc000
	s_mov_b32 s47, 0x24000
	s_mov_b32 s52, 0x3c000
	s_mov_b32 s53, 0x5040100
	s_cbranch_scc0 .LBB0_481
	v_readfirstlane_b32 s3, v220
	s_ashr_i32 s6, s3, 6
	s_cmp_lt_u32 s6, 4
	s_cbranch_scc1 .Lprio_m3_done
	s_setprio 1
.Lprio_m3_done:
	s_mul_i32 s2, s6, 0x4800
	v_readlane_b32 s4, v254, 0
	s_add_i32 s2, s2, 0
	s_ashr_i32 s3, s3, 8
	s_add_i32 s6, s6, s4
	s_cmpk_lt_i32 s6, 0x2000
	v_readlane_b32 s14, v255, 28
	s_cselect_b64 s[4:5], -1, 0
	s_add_i32 s7, s14, 5
	v_readlane_b32 s15, v255, 29
	s_cmp_gt_u32 s7, 12
	v_readlane_b32 s20, v255, 26
	s_cselect_b64 s[14:15], -1, 0
	s_lshl_b32 s36, s20, 8
	s_ashr_i32 s37, s36, 31
	s_add_u32 s60, s78, 0x3300000
	s_addc_u32 s61, s79, 0
	s_add_u32 s62, s78, 0x3400000
	s_addc_u32 s63, s79, 0
	s_add_u32 s7, s78, 0x3900000
	s_addc_u32 s28, s79, 0
	s_add_u32 s82, s78, 0x18000000
	v_and_b32_e32 v132, 63, v221
	s_addc_u32 s83, s79, 0
	s_mov_b32 s64, 0
	v_readlane_b32 s21, v255, 27
	s_branch .LBB0_171

; #define LAS __attribute__((address_space(3)))
; #define WAVE_ITEM_LOOP(COND, CALL) do { \
;         for (int it = blockIdx.x * 8 + wave; it < BATCH * NCH * 16; it += gridDim.x * 8) { \
;             const int bc = it >> 4, k = ((it & 15) + (it >> 8) + 4 * (it >> 11)) & 15, b = bc / NCH, ck_ = bc % NCH; if (!(COND)) continue; \
;             int lane = c.tid & 63; asm volatile("" : "+v"(lane)); CALL; } } while (0)
; template <int pass>
; __device__ __forceinline__ void mix_phase(const Args& a, const MixCtx& c) {
;     ...
;     const int wave = __builtin_amdgcn_readfirstlane(c.tid >> 6);
;     LAS unsigned char* wl = c.lds + wave * WLDS;
;     ...
; #pragma unroll 1
;     for (int st = 0; st < 3; ++st) {
;         const int kind = (st + (wave >> 2)) % 3;
;         if (kind == 0) { if (pass == 1) WAVE_ITEM_LOOP(k >= 8 && k < 12, w_ret_m1(c.ws, c.proj, wl, b, ck_, k - 8, lane)); else WAVE_ITEM_LOOP(k >= 8 && k < 12, w_ret_m3(a, c.l, c.ws, c.proj, c.y, wl, b, ck_, k - 8, lane)); }
;         else if (kind == 1) { if (pass == 1) WAVE_ITEM_LOOP(k >= 12, w_hg_m1(a, c.l, c.ws, c.proj, wl, b, ck_, k - 12, lane)); else WAVE_ITEM_LOOP(k >= 12, w_hg_m3(a, c.l, c.ws, c.proj, c.y, wl, b, ck_, k - 12, lane)); }
;         else { if (pass == 1) WAVE_ITEM_LOOP(k < 8, w_lru_m1(a, c.l, c.ws, c.proj, c.y, wl, b, ck_, k, lane)); else WAVE_ITEM_LOOP(k < 8, w_lru_m3(c.ws, c.proj, c.y, b, ck_, k, lane)); }
.LBB0_500:
	s_andn2_b64 vcc, exec, s[4:5]
	s_cbranch_vccnz .LBB0_824
	v_readfirstlane_b32 s2, v220
	s_ashr_i32 s3, s2, 6
	s_cmp_lt_u32 s3, 4
	s_cbranch_scc1 .Lprio_m1_done
	s_setprio 1
.Lprio_m1_done:
	s_ashr_i32 s2, s2, 8
	s_mul_i32 s4, s3, 0x4800
	v_writelane_b32 v255, s2, 30
	v_readlane_b32 s2, v254, 0
	s_add_i32 s6, s4, 0
	s_add_i32 s2, s3, s2
	s_cmpk_lt_i32 s2, 0x2000
	v_writelane_b32 v255, s2, 31
	s_cselect_b64 s[2:3], -1, 0
	v_writelane_b32 v255, s2, 32
	v_and_b32_e32 v144, 63, v221
	s_mov_b32 s65, 0
	v_writelane_b32 v255, s3, 33
	s_nop 0
	v_readlane_b32 s2, v255, 28
	s_add_i32 s2, s2, 5
	s_cmp_gt_u32 s2, 12
	s_cselect_b64 s[36:37], -1, 0
	s_add_u32 s14, s78, 0x3a00000
	s_addc_u32 s15, s79, 0
	s_add_u32 s7, s78, 0x1c000000
	s_addc_u32 s66, s79, 0
	s_add_u32 s4, s78, 0x3300000
	s_addc_u32 s5, s79, 0
	v_readlane_b32 s3, v255, 29
	s_add_u32 s82, s78, 0x3400000
	s_addc_u32 s83, s79, 0
	v_readlane_b32 s2, v255, 26
	s_add_u32 s67, s78, 0x1a000000
	v_readlane_b32 s3, v255, 27
	s_addc_u32 s28, s79, 0
	s_mov_b32 s34, s2
	s_ashr_i32 s35, s2, 31
	s_lshl_b32 s20, s2, 9
	v_writelane_b32 v255, s2, 26
	s_lshl_b64 s[96:97], s[34:35], 13
	s_ashr_i32 s21, s20, 31
	v_writelane_b32 v255, s3, 27
	s_lshl_b64 s[2:3], s[34:35], 17
	s_add_u32 s24, s78, s2
	s_addc_u32 s27, s79, s3
	s_add_u32 s2, s24, 0x3200000
	s_addc_u32 s3, s27, 0
	s_add_u32 s68, s24, 0x3210000
	s_addc_u32 s70, s27, 0
	s_add_u32 s71, s78, 0x18000000
	s_addc_u32 s64, s79, 0
	s_add_u32 s84, s78, 0x3700000
	s_addc_u32 s85, s79, 0
	s_add_u32 s86, s78, 0x3800000
	s_addc_u32 s87, s79, 0
	s_lshl_b64 s[88:89], s[20:21], 2
	s_branch .LBB0_503

; #define WAVE_ITEM_LOOP(COND, CALL) do { \
;         for (int it = blockIdx.x * 8 + wave; it < BATCH * NCH * 16; it += gridDim.x * 8) { \
;             const int bc = it >> 4, k = ((it & 15) + (it >> 8) + 4 * (it >> 11)) & 15, b = bc / NCH, ck_ = bc % NCH; if (!(COND)) continue; \
;             int lane = c.tid & 63; asm volatile("" : "+v"(lane)); CALL; } } while (0)
; template <int pass>
; __device__ __forceinline__ void mix_phase(const Args& a, const MixCtx& c) {
;     ...
;     for (int st = 0; st < 3; ++st) {
;         const int kind = (st + (wave >> 2)) % 3;
;         if (kind == 0) { if (pass == 1) WAVE_ITEM_LOOP(k >= 8 && k < 12, w_ret_m1(c.ws, c.proj, wl, b, ck_, k - 8, lane)); else WAVE_ITEM_LOOP(k >= 8 && k < 12, w_ret_m3(a, c.l, c.ws, c.proj, c.y, wl, b, ck_, k - 8, lane)); }
;         else if (kind == 1) { if (pass == 1) WAVE_ITEM_LOOP(k >= 12, w_hg_m1(a, c.l, c.ws, c.proj, wl, b, ck_, k - 12, lane)); else WAVE_ITEM_LOOP(k >= 12, w_hg_m3(a, c.l, c.ws, c.proj, c.y, wl, b, ck_, k - 12, lane)); }
;         else { if (pass == 1) WAVE_ITEM_LOOP(k < 8, w_lru_m1(a, c.l, c.ws, c.proj, c.y, wl, b, ck_, k, lane)); else WAVE_ITEM_LOOP(k < 8, w_lru_m3(c.ws, c.proj, c.y, b, ck_, k, lane)); }
;     }
;     ...
;     if (pass == 3) { WAVE_ITEM_LOOP(k >= 8 && k < 12, w_ret_m3(a, c.l, c.ws, c.proj, c.y, wl, b, ck_, k - 8, lane)); WAVE_ITEM_LOOP(k >= 12, w_hg_m3(a, c.l, c.ws, c.proj, c.y, wl, b, ck_, k - 12, lane)); }
;     ...
; }
.LBB0_824:
	s_setprio 0
	s_load_dwordx2 s[62:63], s[0:1], 0xa8
	s_load_dwordx4 s[64:67], s[0:1], 0xa0
	v_readlane_b32 s82, v255, 28
	v_readlane_b32 s84, v255, 22
	v_readlane_b32 s81, v255, 17
	v_readlane_b32 s83, v255, 29
	v_readlane_b32 s89, v255, 18
	v_readlane_b32 s92, v255, 19
	v_readlane_b32 s93, v255, 20
	v_readlane_b32 s96, v255, 21
	v_readlane_b32 s85, v255, 23
	s_movk_i32 s61, 0xc1
	s_waitcnt lgkmcnt(0)
	s_mov_b32 s64, 0x8000
	s_brev_b32 s65, 32
	s_movk_i32 s68, 0x7fff
	s_mov_b32 s70, 0xb00000
	s_movk_i32 s86, 0xf000
	s_movk_i32 s97, 0x2000
	s_mov_b32 s71, 0x12000
	s_mov_b32 s80, 0x14000
	s_mov_b32 s87, 0x16000
	s_movk_i32 s88, 0x4000
	s_cbranch_execnz .LBB0_841
